# XCD-local spin barriers after the first one: all activations are produced and consumed on one XCD (diff-attention units remapped by batch); runtime guard on placement (per-XCC group masks, single deci
# speedup vs baseline: 1.0375x; 1.0375x over previous
.LBB0_90:
	s_or_b64 exec, exec, s[6:7]
	s_lshl_b32 s3, s2, 3
	s_add_i32 s8, s80, s3
	s_cmpk_lt_i32 s2, 0x240
	s_cselect_b64 s[6:7], -1, 0
	v_writelane_b32 v253, s6, 5
	s_ashr_i32 s3, s2, 31
	s_ashr_i32 s83, s54, 31
	v_writelane_b32 v253, s7, 6
	s_lshr_b32 s6, s3, 29
	s_add_i32 s7, s2, s6
	s_ashr_i32 s6, s7, 3
	s_and_b32 s7, s7, -8
	s_sub_i32 s7, s2, s7
	s_cmpk_lt_i32 s54, 0x80
	s_cselect_b64 s[12:13], -1, 0
	v_writelane_b32 v253, s12, 7
	s_movk_i32 s87, 0x49
	v_mov_b32_e32 v1, 0
	v_writelane_b32 v253, s13, 8
	v_writelane_b32 v255, s84, 0
	v_readlane_b32 s12, v253, 1
	s_add_i32 s9, s12, 0x480
	s_cmpk_lt_i32 s12, 0x1280
	v_readlane_b32 s13, v253, 2
	v_writelane_b32 v253, s9, 9
	s_cselect_b64 s[14:15], -1, 0
	v_writelane_b32 v253, s14, 10
	s_cmpk_lt_i32 s12, 0x1700
	s_cselect_b64 s[12:13], -1, 0
	v_writelane_b32 v253, s15, 11
	v_writelane_b32 v253, s12, 12
	s_cmp_gt_i32 s2, 63
	v_writelane_b32 v255, s85, 1
	v_writelane_b32 v253, s13, 13
	s_cselect_b64 s[12:13], -1, 0
	v_writelane_b32 v253, s12, 14
	s_add_i32 s9, s8, 0xfffffe00
	s_addk_i32 s8, 0x280
	v_writelane_b32 v253, s13, 15
	s_cmpk_lt_i32 s9, 0x1280
	v_writelane_b32 v253, s8, 16
	s_cselect_b64 s[12:13], -1, 0
	v_writelane_b32 v253, s12, 17
	s_add_i32 s73, s85, 0xfffffe00
	s_cmpk_lt_i32 s9, 0x1700
	v_writelane_b32 v253, s13, 18
	v_writelane_b32 v253, s9, 19
	s_cselect_b64 s[8:9], -1, 0
	s_add_u32 s66, s0, 0x1200
	s_addc_u32 s67, s1, 0
	s_add_u32 s68, s0, 0x1400
	s_addc_u32 s69, s1, 0
	s_add_u32 s70, s0, 0x1500
	s_addc_u32 s71, s1, 0
	s_add_u32 s74, s0, 0x1600
	s_addc_u32 s75, s1, 0
	s_add_u32 s76, s0, 0x1700
	v_writelane_b32 v253, s8, 20
	s_addc_u32 s77, s1, 0
	v_writelane_b32 v255, s73, 2
	v_writelane_b32 v253, s9, 21
	s_add_u32 s8, s0, 0x1800
	s_addc_u32 s9, s1, 0
	v_writelane_b32 v253, s8, 22
	v_mov_b32_e32 v214, 0x358637bd
	v_mbcnt_hi_u32_b32 v252, -1, v76
	v_writelane_b32 v253, s9, 23
	s_add_u32 s8, s0, 0x1900
	s_addc_u32 s9, s1, 0
	v_writelane_b32 v253, s8, 24
	v_mov_b32_e32 v246, 0x1200
	v_mov_b64_e32 v[248:249], 0x100
	v_writelane_b32 v253, s9, 25
	s_add_u32 s8, s0, 0x1a00
	s_addc_u32 s9, s1, 0
	v_writelane_b32 v253, s8, 26
	s_movk_i32 s72, 0x2000
	s_mov_b32 s97, 0x1fffe0
	v_writelane_b32 v253, s9, 27
	s_add_u32 s8, s0, 0x1b00
	s_addc_u32 s9, s1, 0
	v_writelane_b32 v253, s8, 28
	s_mov_b32 s61, 0x10000
	s_mov_b32 s90, 0x800000
	v_writelane_b32 v253, s9, 29
	s_add_u32 s8, s0, 0x1c00
	s_addc_u32 s9, s1, 0
	v_writelane_b32 v253, s8, 30
	s_movk_i32 s91, 0x1200
	s_movk_i32 s33, 0x90
	v_writelane_b32 v253, s9, 31
	s_add_u32 s8, s0, 0x1d00
	s_addc_u32 s9, s1, 0
	v_writelane_b32 v253, s8, 32
	s_movk_i32 s92, 0x7fff
	s_movk_i32 s94, 0x1600
	v_writelane_b32 v253, s9, 33
	s_add_u32 s8, s0, 0x1e00
	s_addc_u32 s9, s1, 0
	v_writelane_b32 v253, s8, 34
	s_movk_i32 s95, 0x2400
	s_movk_i32 s96, 0x101
	v_writelane_b32 v253, s9, 35
	s_add_u32 s8, s0, 0x1f00
	s_addc_u32 s9, s1, 0
	v_writelane_b32 v253, s8, 36
	s_mov_b32 s52, 0
	s_mov_b64 s[88:89], 0
	v_writelane_b32 v253, s9, 37
	s_add_u32 s8, s0, 0x2000
	s_addc_u32 s9, s1, 0
	v_writelane_b32 v253, s8, 38
	s_mov_b64 s[14:15], -1
	s_mov_b64 s[28:29], 0x80
	v_writelane_b32 v253, s9, 39
	s_add_u32 s8, s0, 0x2100
	s_addc_u32 s9, s1, 0
	v_writelane_b32 v253, s8, 40
	s_mov_b64 s[34:35], 0x24000
	s_mov_b64 s[36:37], 0x48000
	v_writelane_b32 v253, s9, 41
	s_add_u32 s8, s0, 0x2200
	s_addc_u32 s9, s1, 0
	v_writelane_b32 v253, s8, 42
	s_nop 1
	v_writelane_b32 v253, s9, 43
	s_add_u32 s8, s0, 0x2300
	s_addc_u32 s9, s1, 0
	v_writelane_b32 v253, s8, 44
	s_cmp_eq_u32 s11, 15
	s_nop 0
	v_writelane_b32 v253, s9, 45
	s_cselect_b64 s[8:9], -1, 0
	v_writelane_b32 v253, s8, 46
	s_cmp_eq_u32 s11, 14
	s_nop 0
	v_writelane_b32 v253, s9, 47
	s_cselect_b64 s[8:9], -1, 0
	v_writelane_b32 v253, s8, 48
	s_cmp_eq_u32 s11, 13
	s_nop 0
	v_writelane_b32 v253, s9, 49
	s_cselect_b64 s[8:9], -1, 0
	v_writelane_b32 v253, s8, 50
	s_cmp_eq_u32 s11, 12
	s_nop 0
	v_writelane_b32 v253, s9, 51
	s_cselect_b64 s[8:9], -1, 0
	v_writelane_b32 v253, s8, 52
	s_cmp_eq_u32 s11, 11
	s_nop 0
	v_writelane_b32 v253, s9, 53
	s_cselect_b64 s[8:9], -1, 0
	v_writelane_b32 v253, s8, 54
	s_cmp_eq_u32 s11, 10
	s_nop 0
	v_writelane_b32 v253, s9, 55
	s_cselect_b64 s[8:9], -1, 0
	v_writelane_b32 v253, s8, 56
	s_cmp_eq_u32 s11, 9
	s_nop 0
	v_writelane_b32 v253, s9, 57
	s_cselect_b64 s[8:9], -1, 0
	v_writelane_b32 v253, s8, 58
	s_cmp_eq_u32 s11, 8
	s_nop 0
	v_writelane_b32 v253, s9, 59
	s_cselect_b64 s[8:9], -1, 0
	v_writelane_b32 v253, s8, 60
	s_cmp_eq_u32 s11, 7
	s_nop 0
	v_writelane_b32 v253, s9, 61
	s_cselect_b64 s[8:9], -1, 0
	v_writelane_b32 v253, s8, 62
	s_cmp_eq_u32 s11, 6
	s_nop 0
	v_writelane_b32 v253, s9, 63
	s_cselect_b64 s[8:9], -1, 0
	v_writelane_b32 v254, s8, 0
	s_cmp_eq_u32 s11, 5
	s_nop 0
	v_writelane_b32 v254, s9, 1
	s_cselect_b64 s[8:9], -1, 0
	v_writelane_b32 v254, s8, 2
	s_cmp_eq_u32 s11, 4
	s_nop 0
	v_writelane_b32 v254, s9, 3
	s_cselect_b64 s[8:9], -1, 0
	v_writelane_b32 v254, s8, 4
	s_cmp_eq_u32 s11, 3
	s_nop 0
	v_writelane_b32 v254, s9, 5
	s_cselect_b64 s[8:9], -1, 0
	v_writelane_b32 v254, s8, 6
	s_cmp_eq_u32 s11, 2
	s_nop 0
	v_writelane_b32 v254, s9, 7
	s_cselect_b64 s[8:9], -1, 0
	v_writelane_b32 v254, s8, 8
	s_cmp_eq_u32 s11, 1
	s_nop 0
	v_writelane_b32 v254, s9, 9
	s_cselect_b64 s[8:9], -1, 0
	v_writelane_b32 v254, s8, 10
	s_cmp_eq_u32 s11, 0
	s_nop 0
	v_writelane_b32 v254, s9, 11
	s_cselect_b64 s[8:9], -1, 0
	v_writelane_b32 v254, s8, 12
	s_nop 1
	v_writelane_b32 v254, s9, 13
	s_lshl_b32 s8, s10, 2
	s_add_u32 s4, s4, s8
	s_addc_u32 s5, s5, 0
	s_add_u32 s8, s4, 0x1400
	s_addc_u32 s9, s5, 0
	v_writelane_b32 v254, s8, 14
	s_add_u32 s4, s4, 0x2400
	s_addc_u32 s5, s5, 0
	v_writelane_b32 v254, s9, 15
	v_writelane_b32 v254, s4, 16
	s_nop 1
	v_writelane_b32 v254, s5, 17
	s_add_u32 s4, s0, 0x4400
	s_addc_u32 s5, s1, 0
	v_writelane_b32 v254, s4, 18
	s_add_u32 s0, s0, 0x4500
	s_addc_u32 s1, s1, 0
	v_writelane_b32 v254, s5, 19
	v_writelane_b32 v254, s0, 20
	s_cmpk_lt_i32 s84, 0x200
	s_nop 0
	v_writelane_b32 v254, s1, 21
	s_load_dword s1, s[62:63], 0xb0
	s_mul_i32 s0, s55, s54
	s_waitcnt lgkmcnt(0)
	s_mul_i32 s86, s0, s1
	s_cselect_b64 s[0:1], -1, 0
	v_writelane_b32 v254, s0, 22
	s_cmpk_lt_i32 s84, 0x100
	v_writelane_b32 v255, s86, 3
	v_writelane_b32 v254, s1, 23
	s_cselect_b64 s[0:1], -1, 0
	v_writelane_b32 v254, s0, 24
	s_cmpk_lt_i32 s2, 0x100
	s_nop 0
	v_writelane_b32 v254, s1, 25
	s_cselect_b64 s[0:1], -1, 0
	v_writelane_b32 v254, s0, 26
	s_nop 1
	v_writelane_b32 v254, s1, 27
	s_lshl_b32 s0, s7, 5
	s_cmpk_lt_i32 s2, 0x580
	s_cselect_b64 s[4:5], -1, 0
	s_cmp_lt_i32 s7, 0
	s_mul_i32 s1, s7, 33
	v_writelane_b32 v254, s4, 28
	s_cselect_b32 s0, s1, s0
	s_cselect_b32 s1, s87, 0x48
	v_writelane_b32 v254, s5, 29
	s_mul_i32 s1, s7, s1
	s_movk_i32 s4, 0xb1
	s_cselect_b32 s4, s4, 0xb0
	s_add_i32 s1, s1, s6
	s_mul_hi_i32 s5, s1, 0x38e38e39
	s_lshr_b32 s8, s5, 31
	s_ashr_i32 s5, s5, 3
	s_add_i32 s5, s5, s8
	s_mul_i32 s8, s5, 36
	s_sub_i32 s1, s1, s8
	s_bfe_i32 s8, s1, 0x80000
	s_bfe_u32 s8, s8, 0x2000d
	s_add_i32 s8, s1, s8
	s_and_b32 s9, s8, 0xfc
	s_add_i32 s0, s0, s6
	s_sub_i32 s1, s1, s9
	s_ashr_i32 s9, s0, 31
	s_lshr_b32 s9, s9, 28
	s_add_i32 s9, s0, s9
	s_and_b32 s10, s9, 0xfff0
	s_sub_i32 s0, s0, s10
	s_bfe_i32 s10, s0, 0x80000
	s_bfe_u32 s10, s10, 0x2000d
	s_add_i32 s10, s0, s10
	s_and_b32 s11, s10, 0xfc
	s_sub_i32 s11, s0, s11
	s_mul_i32 s0, s7, s4
	s_add_i32 s0, s0, s6
	s_mul_hi_i32 s4, s0, 0x2e8ba2e9
	s_lshr_b32 s6, s4, 31
	s_ashr_i32 s4, s4, 4
	s_add_i32 s4, s4, s6
	s_mul_i32 s6, s4, 0x58
	s_sub_i32 s0, s0, s6
	s_bfe_i32 s6, s0, 0x80000
	s_bfe_u32 s6, s6, 0x2000d
	s_add_i32 s6, s0, s6
	s_and_b32 s7, s6, 0xfc
	s_sub_i32 s7, s0, s7
	s_lshl_b32 s0, s5, 2
	s_bfe_i32 s5, s8, 0x80000
	s_sext_i32_i16 s5, s5
	s_sext_i32_i8 s1, s1
	s_add_i32 s12, s0, s1
	s_ashr_i32 s0, s5, 2
	v_writelane_b32 v254, s0, 30
	s_lshr_b32 s0, s5, 2
	s_bfe_i64 s[0:1], s[0:1], 0x100000
	s_lshl_b64 s[0:1], s[0:1], 19
	v_writelane_b32 v254, s0, 31
	s_sext_i32_i8 s5, s11
	s_ashr_i32 s13, s12, 31
	v_writelane_b32 v254, s1, 32
	s_ashr_i32 s0, s9, 4
	s_lshl_b32 s0, s0, 2
	s_bfe_i32 s1, s10, 0x80000
	s_sext_i32_i16 s1, s1
	s_add_i32 s8, s0, s5
	s_lshl_b32 s0, s4, 2
	s_sext_i32_i8 s5, s7
	s_bfe_i32 s4, s6, 0x80000
	s_add_i32 s6, s0, s5
	s_lshr_b32 s0, s1, 2
	s_ashr_i32 s93, s1, 2
	s_bfe_i64 s[0:1], s[0:1], 0x100000
	s_lshl_b64 s[0:1], s[0:1], 19
	s_sext_i32_i16 s4, s4
	v_writelane_b32 v254, s0, 33
	s_ashr_i32 s9, s8, 31
	s_ashr_i32 s7, s6, 31
	v_writelane_b32 v254, s1, 34
	s_ashr_i32 s0, s4, 2
	v_writelane_b32 v254, s0, 35
	s_lshr_b32 s0, s4, 2
	s_bfe_i64 s[0:1], s[0:1], 0x100000
	s_lshl_b64 s[0:1], s[0:1], 19
	v_writelane_b32 v254, s0, 36
	v_writelane_b32 v255, s93, 4
	s_nop 0
	v_writelane_b32 v254, s1, 37
	s_add_i32 s0, 0, 0x21000
	v_writelane_b32 v254, s0, 38
	s_add_i32 s0, 0, 0x21004
	v_writelane_b32 v254, s0, 39
	s_mov_b32 s0, s12
	v_writelane_b32 v254, s0, 40
	s_nop 1
	v_writelane_b32 v254, s1, 41
	s_lshl_b64 s[0:1], s[12:13], 19
	v_writelane_b32 v254, s0, 42
	s_nop 1
	v_writelane_b32 v254, s1, 43
	s_mov_b32 s0, s8
	v_writelane_b32 v254, s0, 44
	s_nop 1
	v_writelane_b32 v254, s1, 45
	s_lshl_b64 s[0:1], s[8:9], 19
	v_writelane_b32 v254, s0, 46
	s_nop 1
	v_writelane_b32 v254, s1, 47
	s_mov_b32 s0, s6
	v_writelane_b32 v254, s0, 48
	s_nop 1
	v_writelane_b32 v254, s1, 49
	s_lshl_b64 s[0:1], s[6:7], 19
	v_writelane_b32 v254, s0, 50
	s_nop 1
	v_writelane_b32 v254, s1, 51
	v_writelane_b32 v254, s64, 52
	s_nop 1
	v_writelane_b32 v254, s65, 53
	v_writelane_b32 v254, s66, 54
	s_nop 1
	v_writelane_b32 v254, s67, 55
	v_writelane_b32 v254, s68, 56
	s_nop 1
	v_writelane_b32 v254, s69, 57
	v_writelane_b32 v254, s70, 58
	s_nop 1
	v_writelane_b32 v254, s71, 59
	v_writelane_b32 v254, s74, 60
	s_nop 1
	v_writelane_b32 v254, s75, 61
	v_writelane_b32 v254, s76, 62
	s_nop 1
	v_writelane_b32 v254, s77, 63
	v_writelane_b32 v255, 0, 40
	s_branch .LBB0_94

.LBB0_326:
	s_mov_b64 s[6:7], exec
	v_mbcnt_lo_u32_b32 v0, s6, 0
	v_mbcnt_hi_u32_b32 v0, s7, v0
	v_cmp_eq_u32_e32 vcc, 0, v0
	s_and_saveexec_b64 s[4:5], vcc
	s_cbranch_execz .LBB0_328
	s_bcnt1_i32_b64 s6, s[6:7]
	v_mov_b32_e32 v4, s6
	v_readlane_b32 s12, v254, 16
	v_readlane_b32 s13, v254, 17
	s_lshr_b32 s14, s84, 5
	s_lshl_b32 s14, 1, s14
	s_sub_u32 s12, s12, 0x1f80
	s_subb_u32 s13, s13, 0
	v_mov_b32_e32 v5, s14
	s_nop 1
	global_atomic_or v1, v5, s[12:13]
	s_waitcnt vmcnt(0)
	v_readlane_b32 s6, v254, 14
	v_readlane_b32 s7, v254, 15
	s_nop 4
	global_atomic_add v4, v1, v4, s[6:7] sc0
	buffer_inv sc1

.LBB0_342:
	s_andn2_saveexec_b64 s[4:5], s[4:5]
	s_cbranch_execz .LBB0_362
	s_mov_b64 s[4:5], exec
	v_readlane_b32 s12, v255, 40
	s_nop 1
	s_cmp_eq_u32 s12, 0
	s_cbranch_scc1 .Lxb0_glob
	v_readlane_b32 s12, v254, 16
	v_readlane_b32 s13, v254, 17
	v_mov_b32_e32 v0, 1
	s_nop 4
	global_atomic_add v1, v0, s[12:13]
	s_waitcnt vmcnt(0)
	s_branch .LBB0_362
.Lxb0_glob:
	buffer_wbl2 sc1
	s_waitcnt lgkmcnt(0)
	s_waitcnt vmcnt(0)
	v_mbcnt_lo_u32_b32 v0, s4, 0
	v_mbcnt_hi_u32_b32 v0, s5, v0
	v_cmp_eq_u32_e32 vcc, 0, v0
	s_and_saveexec_b64 s[6:7], vcc
	s_cbranch_execz .LBB0_345
	s_bcnt1_i32_b64 s4, s[4:5]
	v_mov_b32_e32 v3, s4
	v_readlane_b32 s4, v254, 18
	v_readlane_b32 s5, v254, 19
	s_nop 4
	global_atomic_add v3, v1, v3, s[4:5] sc0

.LBB0_357:
	s_or_b64 exec, exec, s[4:5]
	s_and_saveexec_b64 s[4:5], s[6:7]
	s_cbranch_execz .LBB0_359
	s_add_u32 s12, s66, 0x800
	s_addc_u32 s13, s67, 0
	v_mov_b32_e32 v12, 0
	v_mov_b32_e32 v14, 0
	global_load_dword v4, v1, s[12:13] offset:-1536 sc1
	global_load_dword v5, v1, s[12:13] offset:-1280 sc1
	global_load_dword v6, v1, s[12:13] offset:-1024 sc1
	global_load_dword v7, v1, s[12:13] offset:-768 sc1
	global_load_dword v8, v1, s[12:13] offset:-512 sc1
	global_load_dword v9, v1, s[12:13] offset:-256 sc1
	global_load_dword v10, v1, s[12:13] offset:0 sc1
	global_load_dword v11, v1, s[12:13] offset:256 sc1
	s_waitcnt vmcnt(0)
	v_or_b32_e32 v12, v12, v4
	v_or_b32_e32 v12, v12, v5
	v_or_b32_e32 v12, v12, v6
	v_or_b32_e32 v12, v12, v7
	v_or_b32_e32 v12, v12, v8
	v_or_b32_e32 v12, v12, v9
	v_or_b32_e32 v12, v12, v10
	v_or_b32_e32 v12, v12, v11
	global_load_dword v4, v1, s[12:13] offset:512 sc1
	global_load_dword v5, v1, s[12:13] offset:768 sc1
	global_load_dword v6, v1, s[12:13] offset:1024 sc1
	global_load_dword v7, v1, s[12:13] offset:1280 sc1
	global_load_dword v8, v1, s[12:13] offset:1536 sc1
	global_load_dword v9, v1, s[12:13] offset:1792 sc1
	global_load_dword v10, v1, s[12:13] offset:2048 sc1
	global_load_dword v11, v1, s[12:13] offset:2304 sc1
	s_waitcnt vmcnt(0)
	v_or_b32_e32 v12, v12, v4
	v_or_b32_e32 v12, v12, v5
	v_or_b32_e32 v12, v12, v6
	v_or_b32_e32 v12, v12, v7
	v_or_b32_e32 v12, v12, v8
	v_or_b32_e32 v12, v12, v9
	v_or_b32_e32 v12, v12, v10
	v_or_b32_e32 v12, v12, v11
	global_load_dword v4, v1, s[12:13] offset:-1408 sc1
	global_load_dword v5, v1, s[12:13] offset:-1152 sc1
	global_load_dword v6, v1, s[12:13] offset:-896 sc1
	global_load_dword v7, v1, s[12:13] offset:-640 sc1
	global_load_dword v8, v1, s[12:13] offset:-384 sc1
	global_load_dword v9, v1, s[12:13] offset:-128 sc1
	global_load_dword v10, v1, s[12:13] offset:128 sc1
	global_load_dword v11, v1, s[12:13] offset:384 sc1
	s_waitcnt vmcnt(0)
	v_add_u32_e32 v13, -1, v4
	v_and_b32_e32 v13, v13, v4
	v_or_b32_e32 v14, v14, v13
	v_add_u32_e32 v13, -1, v5
	v_and_b32_e32 v13, v13, v5
	v_or_b32_e32 v14, v14, v13
	v_add_u32_e32 v13, -1, v6
	v_and_b32_e32 v13, v13, v6
	v_or_b32_e32 v14, v14, v13
	v_add_u32_e32 v13, -1, v7
	v_and_b32_e32 v13, v13, v7
	v_or_b32_e32 v14, v14, v13
	v_add_u32_e32 v13, -1, v8
	v_and_b32_e32 v13, v13, v8
	v_or_b32_e32 v14, v14, v13
	v_add_u32_e32 v13, -1, v9
	v_and_b32_e32 v13, v13, v9
	v_or_b32_e32 v14, v14, v13
	v_add_u32_e32 v13, -1, v10
	v_and_b32_e32 v13, v13, v10
	v_or_b32_e32 v14, v14, v13
	v_add_u32_e32 v13, -1, v11
	v_and_b32_e32 v13, v13, v11
	v_or_b32_e32 v14, v14, v13
	global_load_dword v4, v1, s[12:13] offset:640 sc1
	global_load_dword v5, v1, s[12:13] offset:896 sc1
	global_load_dword v6, v1, s[12:13] offset:1152 sc1
	global_load_dword v7, v1, s[12:13] offset:1408 sc1
	global_load_dword v8, v1, s[12:13] offset:1664 sc1
	global_load_dword v9, v1, s[12:13] offset:1920 sc1
	global_load_dword v10, v1, s[12:13] offset:2176 sc1
	global_load_dword v11, v1, s[12:13] offset:2432 sc1
	s_waitcnt vmcnt(0)
	v_add_u32_e32 v13, -1, v4
	v_and_b32_e32 v13, v13, v4
	v_or_b32_e32 v14, v14, v13
	v_add_u32_e32 v13, -1, v5
	v_and_b32_e32 v13, v13, v5
	v_or_b32_e32 v14, v14, v13
	v_add_u32_e32 v13, -1, v6
	v_and_b32_e32 v13, v13, v6
	v_or_b32_e32 v14, v14, v13
	v_add_u32_e32 v13, -1, v7
	v_and_b32_e32 v13, v13, v7
	v_or_b32_e32 v14, v14, v13
	v_add_u32_e32 v13, -1, v8
	v_and_b32_e32 v13, v13, v8
	v_or_b32_e32 v14, v14, v13
	v_add_u32_e32 v13, -1, v9
	v_and_b32_e32 v13, v13, v9
	v_or_b32_e32 v14, v14, v13
	v_add_u32_e32 v13, -1, v10
	v_and_b32_e32 v13, v13, v10
	v_or_b32_e32 v14, v14, v13
	v_add_u32_e32 v13, -1, v11
	v_and_b32_e32 v13, v13, v11
	v_or_b32_e32 v14, v14, v13
	v_cmp_eq_u32_e32 vcc, 32, v12
	v_cmp_eq_u32_e64 s[14:15], 0, v14
	s_and_b64 vcc, vcc, s[14:15]
	s_nop 1
	v_cndmask_b32_e64 v12, 2, 1, vcc
	v_add_co_u32_e32 v4, vcc, 0xffffef00, v2
	s_nop 1
	v_addc_co_u32_e32 v5, vcc, -1, v3, vcc
	global_atomic_add v[4:5], v12, off offset:4
	global_atomic_add v[4:5], v12, off offset:260
	global_atomic_add v[4:5], v12, off offset:516
	global_atomic_add v[4:5], v12, off offset:772
	global_atomic_add v[4:5], v12, off offset:1028
	global_atomic_add v[4:5], v12, off offset:1284
	global_atomic_add v[4:5], v12, off offset:1540
	global_atomic_add v[4:5], v12, off offset:1796
	global_atomic_add v[4:5], v12, off offset:2052
	global_atomic_add v[4:5], v12, off offset:2308
	global_atomic_add v[4:5], v12, off offset:2564
	global_atomic_add v[4:5], v12, off offset:2820
	global_atomic_add v[4:5], v12, off offset:3076
	global_atomic_add v[4:5], v12, off offset:3332
	global_atomic_add v[4:5], v12, off offset:3588
	global_atomic_add v[4:5], v12, off offset:3844
	s_waitcnt vmcnt(0)
	v_mov_b32_e32 v0, 1
	global_atomic_add v[2:3], v0, off
	v_add_co_u32_e32 v2, vcc, 0xffffef00, v2
	s_nop 1
	v_addc_co_u32_e32 v3, vcc, -1, v3, vcc
	global_atomic_add v[2:3], v0, off
	global_atomic_add v[2:3], v0, off offset:256
	global_atomic_add v[2:3], v0, off offset:512
	global_atomic_add v[2:3], v0, off offset:768
	global_atomic_add v[2:3], v0, off offset:1024
	global_atomic_add v[2:3], v0, off offset:1280
	global_atomic_add v[2:3], v0, off offset:1536
	global_atomic_add v[2:3], v0, off offset:1792
	global_atomic_add v[2:3], v0, off offset:2048
	global_atomic_add v[2:3], v0, off offset:2304
	global_atomic_add v[2:3], v0, off offset:2560
	global_atomic_add v[2:3], v0, off offset:2816
	global_atomic_add v[2:3], v0, off offset:3072
	global_atomic_add v[2:3], v0, off offset:3328
	global_atomic_add v[2:3], v0, off offset:3584
	global_atomic_add v[2:3], v0, off offset:3840

.LBB0_362:
	s_or_b64 exec, exec, s[0:1]
	v_readlane_b32 s12, v254, 16
	v_readlane_b32 s13, v254, 17
	s_mov_b32 s14, 0
	s_nop 4
.Lxb_dec_poll:
	global_load_dword v0, v1, s[12:13] offset:4 sc1
	s_waitcnt vmcnt(0)
	v_readfirstlane_b32 s18, v0
	s_add_i32 s14, s14, 1
	s_cmp_lg_u32 s18, 0
	s_cbranch_scc1 .Lxb_dec_got
	s_sleep 0
	s_cmp_lt_u32 s14, 0x100000
	s_cbranch_scc1 .Lxb_dec_poll
.Lxb_dec_got:
	s_cmp_eq_u32 s18, 1
	s_cselect_b32 s12, 1, 0
	s_nop 0
	v_writelane_b32 v255, s12, 40
	v_writelane_b32 v255, s88, 10
	s_xor_b64 s[0:1], s[88:89], -1
	s_mov_b64 s[4:5], s[62:63]
	v_writelane_b32 v255, s89, 11
	v_writelane_b32 v255, s0, 12
	s_waitcnt lgkmcnt(0)
	s_barrier
	v_and_b32_e32 v0, 63, v247
	v_writelane_b32 v255, s1, 13
	s_load_dwordx2 s[0:1], s[4:5], 0xa0
	s_load_dwordx4 s[48:51], s[4:5], 0x18
	s_load_dwordx8 s[40:47], s[4:5], 0x30
	v_add_u32_e32 v2, s8, v0
	v_ashrrev_i32_e32 v3, 31, v2
	v_lshlrev_b64 v[2:3], 2, v[2:3]
	s_waitcnt lgkmcnt(0)
	v_lshl_add_u64 v[4:5], s[48:49], 0, v[2:3]
	global_load_dword v10, v[4:5], off
	v_lshl_add_u64 v[4:5], s[50:51], 0, v[2:3]
	global_load_dword v11, v[4:5], off
	v_lshl_add_u64 v[4:5], s[40:41], 0, v[2:3]
	global_load_dword v12, v[4:5], off
	v_lshl_add_u64 v[4:5], s[42:43], 0, v[2:3]
	global_load_dword v13, v[4:5], off
	v_and_b32_e32 v14, 64, v252
	v_xor_b32_e32 v4, 1, v252
	v_add_u32_e32 v14, 64, v14
	v_xor_b32_e32 v5, 2, v252
	v_cmp_lt_i32_e32 vcc, v4, v14
	v_xor_b32_e32 v6, 4, v252
	v_xor_b32_e32 v7, 8, v252
	v_cndmask_b32_e32 v4, v252, v4, vcc
	v_cmp_lt_i32_e32 vcc, v5, v14
	s_load_dwordx4 s[8:11], s[4:5], 0x50
	v_xor_b32_e32 v8, 16, v252
	v_cndmask_b32_e32 v5, v252, v5, vcc
	v_cmp_lt_i32_e32 vcc, v6, v14
	v_xor_b32_e32 v9, 32, v252
	v_lshlrev_b32_e32 v15, 2, v5
	v_cndmask_b32_e32 v6, v252, v6, vcc
	v_cmp_lt_i32_e32 vcc, v7, v14
	v_lshlrev_b32_e32 v16, 2, v6
	v_cvt_f32_u32_e32 v0, s52
	v_cndmask_b32_e32 v7, v252, v7, vcc
	v_cmp_lt_i32_e32 vcc, v8, v14
	v_lshlrev_b32_e32 v17, 2, v7
	v_lshl_add_u64 v[6:7], s[46:47], 0, v[2:3]
	v_cndmask_b32_e32 v8, v252, v8, vcc
	v_cmp_lt_i32_e32 vcc, v9, v14
	v_lshlrev_b32_e32 v14, 2, v4
	v_lshlrev_b32_e32 v220, 2, v8
	v_cndmask_b32_e32 v9, v252, v9, vcc
	v_lshlrev_b32_e32 v221, 2, v9
	v_lshl_add_u64 v[4:5], s[44:45], 0, v[2:3]
	s_waitcnt lgkmcnt(0)
	v_lshl_add_u64 v[8:9], s[8:9], 0, v[2:3]
	v_lshl_add_u64 v[2:3], s[10:11], 0, v[2:3]
	global_load_dword v4, v[4:5], off
	s_nop 0
	global_load_dword v5, v[6:7], off
	s_nop 0
	global_load_dword v6, v[8:9], off
	s_nop 0
	global_load_dword v2, v[2:3], off
	v_mul_f32_e32 v0, 0xbe99999a, v0
	v_mul_f32_e32 v0, 0x3fb8aa3b, v0
	v_exp_f32_e32 v0, v0
	v_mov_b32_e32 v3, 0x3f4ccccd
	s_add_u32 s8, s0, 0x5000000
	s_addc_u32 s9, s1, 0
	v_fmamk_f32 v0, v0, 0xbf19999a, v3
	v_readlane_b32 s10, v254, 22
	s_add_u32 s18, s0, 0x9800000
	v_readlane_b32 s11, v254, 23
	s_addc_u32 s19, s1, 0
	s_andn2_b64 vcc, exec, s[10:11]
	s_waitcnt vmcnt(7)
	v_and_b32_e32 v3, 0x7fffffff, v10
	v_max_f32_e64 v7, |v10|, |v10|
	s_waitcnt vmcnt(6)
	v_and_b32_e32 v8, 0x7fffffff, v11
	ds_bpermute_b32 v3, v14, v3
	s_waitcnt vmcnt(5)
	v_and_b32_e32 v10, 0x7fffffff, v12
	ds_bpermute_b32 v8, v14, v8
	ds_bpermute_b32 v10, v14, v10
	v_max_f32_e64 v9, |v11|, |v11|
	s_waitcnt lgkmcnt(2)
	v_max_f32_e32 v3, v3, v3
	v_max_f32_e64 v11, |v12|, |v12|
	s_waitcnt lgkmcnt(1)
	v_max_f32_e32 v8, v8, v8
	s_waitcnt lgkmcnt(0)
	v_max_f32_e32 v10, v10, v10
	v_max_f32_e32 v3, v7, v3
	v_max_f32_e32 v7, v9, v8
	s_waitcnt vmcnt(4)
	v_and_b32_e32 v12, 0x7fffffff, v13
	v_max_f32_e32 v8, v11, v10
	ds_bpermute_b32 v11, v15, v7
	ds_bpermute_b32 v12, v14, v12
	v_max_f32_e64 v13, |v13|, |v13|
	ds_bpermute_b32 v10, v15, v3
	s_waitcnt lgkmcnt(2)
	v_max_f32_e32 v11, v11, v11
	s_waitcnt lgkmcnt(1)
	v_max_f32_e32 v12, v12, v12
	v_max_f32_e32 v7, v7, v11
	v_max_f32_e32 v9, v13, v12
	ds_bpermute_b32 v12, v15, v8
	ds_bpermute_b32 v11, v16, v7
	s_waitcnt lgkmcnt(2)
	v_max_f32_e32 v10, v10, v10
	v_max_f32_e32 v3, v3, v10
	ds_bpermute_b32 v10, v16, v3
	s_waitcnt lgkmcnt(2)
	v_max_f32_e32 v12, v12, v12
	s_waitcnt lgkmcnt(1)
	v_max_f32_e32 v11, v11, v11
	v_max_f32_e32 v8, v8, v12
	v_max_f32_e32 v7, v7, v11
	ds_bpermute_b32 v12, v16, v8
	ds_bpermute_b32 v11, v17, v7
	ds_bpermute_b32 v13, v15, v9
	s_waitcnt lgkmcnt(3)
	v_max_f32_e32 v10, v10, v10
	v_max_f32_e32 v3, v3, v10
	s_waitcnt lgkmcnt(2)
	v_max_f32_e32 v12, v12, v12
	s_waitcnt lgkmcnt(1)
	v_max_f32_e32 v11, v11, v11
	v_max_f32_e32 v8, v8, v12
	v_max_f32_e32 v7, v7, v11
	ds_bpermute_b32 v12, v17, v8
	ds_bpermute_b32 v11, v220, v7
	s_waitcnt lgkmcnt(2)
	v_max_f32_e32 v13, v13, v13
	ds_bpermute_b32 v10, v17, v3
	v_max_f32_e32 v9, v9, v13
	s_waitcnt lgkmcnt(2)
	v_max_f32_e32 v12, v12, v12
	s_waitcnt lgkmcnt(1)
	v_max_f32_e32 v11, v11, v11
	v_max_f32_e32 v8, v8, v12
	v_max_f32_e32 v7, v7, v11
	ds_bpermute_b32 v12, v220, v8
	ds_bpermute_b32 v11, v221, v7
	ds_bpermute_b32 v13, v16, v9
	s_waitcnt lgkmcnt(3)
	v_max_f32_e32 v10, v10, v10
	v_max_f32_e32 v3, v3, v10
	s_waitcnt lgkmcnt(2)
	v_max_f32_e32 v12, v12, v12
	s_waitcnt lgkmcnt(1)
	v_max_f32_e32 v11, v11, v11
	ds_bpermute_b32 v10, v220, v3
	v_max_f32_e32 v8, v8, v12
	v_max_f32_e32 v7, v7, v11
	s_waitcnt lgkmcnt(1)
	v_max_f32_e32 v11, v13, v13
	s_waitcnt vmcnt(2)
	v_mul_f32_e32 v12, v4, v5
	s_waitcnt vmcnt(0)
	v_mul_f32_e32 v13, v6, v2
	ds_bpermute_b32 v12, v14, v12
	ds_bpermute_b32 v13, v14, v13
	s_waitcnt lgkmcnt(2)
	v_max_f32_e32 v10, v10, v10
	v_max_f32_e32 v3, v3, v10
	v_max_f32_e32 v9, v9, v11
	s_waitcnt lgkmcnt(1)
	v_fmac_f32_e32 v12, v4, v5
	s_waitcnt lgkmcnt(0)
	v_fmac_f32_e32 v13, v6, v2
	ds_bpermute_b32 v10, v221, v3
	ds_bpermute_b32 v11, v17, v9
	ds_bpermute_b32 v4, v15, v12
	ds_bpermute_b32 v2, v15, v13
	s_waitcnt lgkmcnt(3)
	v_max_f32_e32 v10, v10, v10
	s_waitcnt lgkmcnt(2)
	v_max_f32_e32 v11, v11, v11
	s_waitcnt lgkmcnt(1)
	v_add_f32_e32 v4, v12, v4
	s_waitcnt lgkmcnt(0)
	v_add_f32_e32 v2, v13, v2
	v_max_f32_e32 v3, v3, v10
	ds_bpermute_b32 v10, v221, v8
	v_max_f32_e32 v5, v9, v11
	ds_bpermute_b32 v9, v16, v4
	ds_bpermute_b32 v11, v16, v2
	ds_bpermute_b32 v6, v220, v5
	s_waitcnt lgkmcnt(3)
	v_max_f32_e32 v10, v10, v10
	v_max_f32_e32 v8, v8, v10
	s_waitcnt lgkmcnt(2)
	v_add_f32_e32 v4, v4, v9
	s_waitcnt lgkmcnt(1)
	v_add_f32_e32 v2, v2, v11
	ds_bpermute_b32 v9, v17, v4
	ds_bpermute_b32 v10, v17, v2
	s_waitcnt lgkmcnt(2)
	v_max_f32_e32 v6, v6, v6
	v_max_f32_e32 v5, v5, v6
	ds_bpermute_b32 v6, v221, v5
	s_waitcnt lgkmcnt(2)
	v_add_f32_e32 v4, v4, v9
	s_waitcnt lgkmcnt(1)
	v_add_f32_e32 v2, v2, v10
	ds_bpermute_b32 v9, v220, v4
	ds_bpermute_b32 v10, v220, v2
	s_waitcnt lgkmcnt(2)
	v_max_f32_e32 v6, v6, v6
	v_max_f32_e32 v5, v5, v6
	v_mul_f32_e32 v3, 0x41000000, v3
	s_waitcnt lgkmcnt(1)
	v_add_f32_e32 v4, v4, v9
	s_waitcnt lgkmcnt(0)
	v_add_f32_e32 v2, v2, v10
	ds_bpermute_b32 v6, v221, v4
	ds_bpermute_b32 v9, v221, v2
	v_mul_f32_e32 v3, v3, v7
	s_waitcnt lgkmcnt(0)
	v_add_f32_e32 v2, v2, v9
	v_readfirstlane_b32 s12, v3
	v_add_f32_e32 v3, v4, v6
	v_mul_f32_e32 v3, 0x3fb8aa3b, v3
	v_mul_f32_e32 v2, 0x3fb8aa3b, v2
	v_exp_f32_e32 v3, v3
	v_exp_f32_e32 v2, v2
	v_mul_f32_e32 v4, 0x41000000, v8
	v_mul_f32_e32 v4, v4, v5
	v_sub_f32_e32 v2, v3, v2
	v_add_f32_e32 v2, v0, v2
	v_readfirstlane_b32 s7, v4
	v_readfirstlane_b32 s6, v2
	s_cbranch_vccnz .LBB0_371
	s_load_dwordx2 s[10:11], s[4:5], 0x60
	v_mov_b32_e32 v2, 0x3fb8aa3b
	s_lshl_b32 s58, s52, 7
	v_mul_f32_e32 v2, s7, v2
	s_lshl_b64 s[14:15], s[58:59], 2
	s_waitcnt lgkmcnt(0)
	s_add_u32 s10, s10, s14
	v_mul_f32_e32 v2, 0xbf828f5c, v2
	v_sub_f32_e32 v190, 1.0, v0
	s_addc_u32 s11, s11, s15
	v_mov_b32_e32 v3, v2
	v_mov_b32_e32 v4, v2
	v_mov_b32_e32 v5, v2
	v_mov_b32_e32 v6, v2
	v_mov_b32_e32 v7, v2
	v_mov_b32_e32 v8, v2
	v_mov_b32_e32 v9, v2
	v_mov_b32_e32 v10, v2
	v_mov_b32_e32 v11, v2
	v_mov_b32_e32 v12, v2
	v_mov_b32_e32 v13, v2
	v_mov_b32_e32 v14, v2
	v_mov_b32_e32 v15, v2
	v_mov_b32_e32 v16, v2
	v_mov_b32_e32 v17, v2
	s_mov_b32 s7, s6
	s_lshr_b32 s13, s84, 5
	s_lshl_b32 s13, s13, 6
	s_and_b32 s14, s84, 31
	s_or_b32 s13, s13, s14
	s_branch .LBB0_365
.LBB0_364:
	s_add_i32 s13, s13, 32
	s_bitcmp0_b32 s13, 5
	v_mov_b32_e32 v246, v222
	v_mov_b32_e32 v247, v215
	s_barrier
	s_cbranch_scc1 .LBB0_371
